# PL1 on PW1: plain weight units: norm-gain load no longer has its own round trip (wait moved behind the four data loads)
# speedup vs baseline: 1.0038x; 1.0021x over previous
; __device__ void p_weights_plain(const Args& a) {
;     ...
;         f32x4 x[4];
; #pragma unroll
;         for (int i = 0; i < 4; ++i) x[i] = *(const f32x4*)(w + (size_t)i * ldw + col) * gn[i];
; #pragma unroll
;         for (int j = 0; j < 4; ++j) {
;             f16x4 o;
; #pragma unroll
;             for (int i = 0; i < 4; ++i) o[i] = (f16)x[i][j];
;             *(f16x4*)(dst + (size_t)j * 1024) = o;
;         }
.LBB0_32:
	s_add_u32 s10, s40, s10
	v_ashrrev_i32_e32 v15, 31, v14
	s_addc_u32 s11, s41, s11
	v_lshl_add_u64 v[14:15], v[14:15], 2, v[18:19]
	s_lshl_b32 s4, s6, 2
	global_load_dwordx4 v[18:21], v[14:15], off
	v_lshl_add_u64 v[14:15], v[14:15], 0, s[4:5]
	global_load_dwordx4 v[22:25], v[14:15], off
	v_lshl_add_u64 v[14:15], v[14:15], 0, s[4:5]
	global_load_dwordx4 v[26:29], v[14:15], off
	v_lshl_add_u64 v[14:15], v[14:15], 0, s[4:5]
	global_load_dwordx4 v[30:33], v[14:15], off
	v_lshl_add_u64 v[14:15], v[16:17], 0, v[6:7]
	v_lshlrev_b64 v[14:15], 11, v[14:15]
	v_lshl_add_u64 v[14:15], s[10:11], 0, v[14:15]
	s_add_i32 s35, s35, s3
	s_add_i32 s9, s9, s12
	s_add_i32 s13, s13, s30
	v_lshl_add_u64 v[8:9], v[8:9], 1, v[14:15]
	s_cmpk_lt_i32 s35, 0x2c0
	v_add_co_u32_e32 v14, vcc, s34, v8
	s_waitcnt vmcnt(3)
	v_mov_b32_e32 v12, v3
	v_mov_b32_e32 v10, v5
	v_pk_mul_f32 v[16:17], v[2:3], v[20:21] op_sel_hi:[0,1]
	v_pk_mul_f32 v[2:3], v[2:3], v[18:19] op_sel_hi:[0,1]
	s_waitcnt vmcnt(2)
	v_pk_mul_f32 v[18:19], v[12:13], v[24:25] op_sel_hi:[0,1]
	v_pk_mul_f32 v[12:13], v[12:13], v[22:23] op_sel_hi:[0,1]
	s_waitcnt vmcnt(1)
	v_pk_mul_f32 v[20:21], v[4:5], v[28:29] op_sel_hi:[0,1]
	v_pk_mul_f32 v[4:5], v[4:5], v[26:27] op_sel_hi:[0,1]
	s_waitcnt vmcnt(0)
	v_pk_mul_f32 v[24:25], v[10:11], v[30:31] op_sel_hi:[0,1]
	v_cvt_pk_f16_f32 v2, v2, v12
	v_cvt_pk_f16_f32 v12, v3, v13
	v_pk_mul_f32 v[22:23], v[10:11], v[32:33] op_sel_hi:[0,1]
	v_cvt_pk_f16_f32 v3, v4, v24
	v_addc_co_u32_e32 v15, vcc, 0, v9, vcc
	v_cvt_pk_f16_f32 v16, v16, v18
	v_cvt_pk_f16_f32 v18, v17, v19
	v_cvt_pk_f16_f32 v13, v5, v25
	v_cvt_pk_f16_f32 v17, v20, v22
	v_cvt_pk_f16_f32 v19, v21, v23
	global_store_dwordx2 v[8:9], v[2:3], off
	global_store_dwordx2 v[8:9], v[12:13], off offset:2048
	global_store_dwordx2 v[14:15], v[16:17], off
	global_store_dwordx2 v[14:15], v[18:19], off offset:2048
	s_cbranch_scc0 .Lws_passend

; __device__ void p_weights_plain(const Args& a) {
;     ...
;         const float* w; f16* dst; int ldw, col; f32x4 gn = {1.f, 1.f, 1.f, 1.f};
;         if (u < 448) {
;             const int l = u / 224, r = u % 224, pn = r >> 5, kblk = r & 31, k0 = kblk * 32 + 4 * rq;
;             const int L = pn * 256 + lc0; col = (L < 1280) ? L : L + 512; ldw = INW;
;             w = a.w_in + (size_t)l * DM * INW + (size_t)k0 * INW;
;             gn = *(const f32x4*)(a.norm_gain + l * DM + k0);
;             dst = W1T + ((size_t)l * N1 + pn * 256 + rho0) * 1024 + k0;
;         } else {
;             const int r = u - 448, l = r >> 7, pn = (r >> 5) & 3, kblk = r & 31, k0 = kblk * 32 + 4 * rq;
;             col = pn * 256 + lc0; ldw = DM;
;             w = a.w_out + (size_t)l * DM * DM + (size_t)k0 * DM;
;             dst = W2T + ((size_t)l * DM + pn * 256 + rho0) * 1024 + k0;
;         }
.LBB0_35:
	s_andn2_b64 vcc, exec, s[6:7]
	s_cbranch_vccz .LBB0_31
	v_mov_b32_e32 v2, 1.0
	s_mov_b64 s[6:7], 0x400
	s_mov_b64 s[10:11], 0x20600000
	v_mov_b32_e32 v3, 1.0
	v_mov_b32_e32 v4, 1.0
	v_mov_b32_e32 v5, 1.0
	s_branch .LBB0_32
